# v104 plus cross-map hoist: last loop step of DA map 0 issues map 1 first K/V tiles and Q loads; map-1 prologue skips them and their waits
# speedup vs baseline: 1.0041x; 1.0002x over previous
; __device__ __forceinline__ void flash_da2(LAS unsigned char* lds, const bf16* __restrict__ Qw, const bf16* __restrict__ Kb, const bf16* __restrict__ VTb,
;                                           int NT, int qpos_w, f32x16 (&o)[4], float& mref, float& lsum) {
;     ...
;     bf16x8 qf[4];
; #pragma unroll
;     for (int d0 = 0; d0 < 4; ++d0) qf[d0] = *(const bf16x8*)(Qw + (size_t)r32 * 64 + d0 * 16 + hi * 8);
;     const int lrow = wid * 8 + (lane >> 3), pch = lane & 7, lch = pch ^ ((lrow >> 1) & 7);
;     const int rho = lrow & 31, key = (lrow & 32) + 16 * ((rho >> 2) & 1) + 4 * (rho >> 3) + (rho & 3);
;     const bf16* ksrc = Kb + key * 64 + lch * 8;
;     const bf16* vsrc = VTb + lrow * 64 + lch * 8;
;     const unsigned kdst = lds0 + A_K + wid * 1024, vdst = lds0 + A_V + wid * 1024;
;     const int sw = (r32 >> 1) & 7;
;     unsigned kaddr[4], vaddr[4];
; #pragma unroll
;     for (int d0 = 0; d0 < 4; ++d0) kaddr[d0] = A_K + r32 * 128 + (((2 * d0 + hi) ^ sw) << 4);
; #pragma unroll
;     for (int c4 = 0; c4 < 4; ++c4) vaddr[c4] = A_V + r32 * 128 + (((4 * (c4 >> 1) + 2 * hi + (c4 & 1)) ^ sw) << 4);
; #pragma unroll
;     for (int j = 0; j < 2; ++j) {
;         glds16(ksrc + (size_t)j * 4096, (unsigned)__builtin_amdgcn_readfirstlane(kdst + j * 8192));
;         glds16(vsrc + (size_t)j * 8192, (unsigned)__builtin_amdgcn_readfirstlane(vdst + j * 16384));
;         glds16(vsrc + (size_t)j * 8192 + 4096, (unsigned)__builtin_amdgcn_readfirstlane(vdst + j * 16384 + 8192));
;     }
;     asm volatile("" :: "v"(qf[0]), "v"(qf[1]), "v"(qf[2]), "v"(qf[3]));
;     asm volatile("s_waitcnt vmcnt(0) lgkmcnt(0)\n\ts_barrier" ::: "memory");
.LBB0_426:
	s_mov_b32 s99, s8
	s_mul_i32 s8, s51, s8
	s_xor_b64 s[58:59], s[10:11], -1
	s_lshl_b64 s[10:11], s[8:9], 1
	v_lshl_add_u64 v[2:3], v[158:159], 0, s[10:11]
	s_cmp_lg_u32 s99, 0
	s_cbranch_scc1 .Lmx_pq
	global_load_dwordx4 v[112:115], v[2:3], off
	global_load_dwordx4 v[116:119], v[2:3], off offset:32
	global_load_dwordx4 v[120:123], v[2:3], off offset:64
	global_load_dwordx4 v[124:127], v[2:3], off offset:96
.Lmx_pq:
	s_add_u32 s52, s88, s10
	v_readfirstlane_b32 s35, v151
	s_addc_u32 s53, s89, s11
	s_lshr_b32 s10, s35, 6
	s_lshl_b32 s11, s10, 3
	s_lshr_b32 s35, s35, 4
	v_or_b32_e32 v0, s11, v195
	s_and_b32 s11, s11, 32
	s_and_b32 s35, s35, 12
	s_or_b32 s11, s11, s35
	v_lshrrev_b32_e32 v8, 1, v0
	v_or_b32_e32 v4, s11, v196
	v_lshlrev_b32_e32 v0, 7, v0
	v_xor_b32_e32 v6, v8, v151
	v_lshl_add_u64 v[2:3], s[54:55], 0, v[0:1]
	v_lshlrev_b32_e32 v0, 7, v4
	v_lshl_add_u64 v[4:5], s[52:53], 0, v[0:1]
	v_lshlrev_b32_e32 v0, 4, v6
	s_lshl_b32 s11, s10, 10
	v_and_b32_e32 v0, 0x70, v0
	s_add_i32 s35, s11, 0
	v_lshl_add_u64 v[4:5], v[4:5], 0, v[0:1]
	v_mov_b64_e32 v[246:247], v[4:5]
	s_mov_b32 s11, m0
	s_mov_b32 m0, s35
	s_nop 0
	s_cmp_lg_u32 s99, 0
	s_cbranch_scc1 .Lmx_pd0
	global_load_lds_dwordx4 v[4:5], off
.Lmx_pd0:
	s_mov_b32 m0, s11
	v_lshl_add_u64 v[2:3], v[2:3], 0, v[0:1]
	v_mov_b64_e32 v[248:249], v[2:3]
	s_add_i32 s52, s35, 0x8000
	s_mov_b32 s11, m0
	s_mov_b32 m0, s52
	s_nop 0
	s_cmp_lg_u32 s99, 0
	s_cbranch_scc1 .Lmx_pd1
	global_load_lds_dwordx4 v[2:3], off
.Lmx_pd1:
	s_mov_b32 m0, s11
	v_lshl_add_u64 v[6:7], v[2:3], 0, s[38:39]
	s_add_i32 s11, s52, 0x2000
	s_mov_b32 s53, m0
	s_mov_b32 m0, s11
	s_nop 0
	s_cmp_lg_u32 s99, 0
	s_cbranch_scc1 .Lmx_pd2
	global_load_lds_dwordx4 v[6:7], off
.Lmx_pd2:
	s_mov_b32 m0, s53
	v_lshl_add_u64 v[6:7], v[4:5], 0, s[38:39]
	s_add_i32 s11, s35, 0x2000
	s_mov_b32 s53, m0
	s_mov_b32 m0, s11
	s_nop 0
	s_cmp_lg_u32 s99, 0
	s_cbranch_scc1 .Lmx_pd3
	global_load_lds_dwordx4 v[6:7], off
.Lmx_pd3:
	s_mov_b32 m0, s53
	v_lshl_add_u64 v[6:7], v[2:3], 0, s[40:41]
	s_add_i32 s11, s35, 0xc000
	s_mov_b32 s53, m0
	s_mov_b32 m0, s11
	s_nop 0
	s_cmp_lg_u32 s99, 0
	s_cbranch_scc1 .Lmx_pd4
	global_load_lds_dwordx4 v[6:7], off
.Lmx_pd4:
	s_mov_b32 m0, s53
	v_lshl_add_u64 v[2:3], v[2:3], 0, s[42:43]
	v_bitop3_b32 v0, v8, 7, v151 bitop3:0x48
	s_add_i32 s11, s35, 0xe000
	s_mov_b32 s53, m0
	s_mov_b32 m0, s11
	s_nop 0
	s_cmp_lg_u32 s99, 0
	s_cbranch_scc1 .Lmx_pd5
	global_load_lds_dwordx4 v[2:3], off
.Lmx_pd5:
	s_mov_b32 m0, s53
	v_lshlrev_b32_e32 v0, 4, v0
	v_lshl_or_b32 v2, s10, 9, v216
	v_mov_b32_e32 v3, v1
	v_lshl_add_u64 v[2:3], v[2:3], 1, v[0:1]
	v_mov_b32_e32 v14, v1
	v_mov_b32_e32 v15, v1
	v_lshl_add_u64 v[160:161], s[56:57], 0, v[2:3]
	v_lshl_add_u64 v[162:163], v[4:5], 0, s[42:43]
	v_mov_b32_e32 v0, v1
	v_mov_b32_e32 v2, v1
	v_mov_b32_e32 v3, v1
	v_mov_b32_e32 v4, v1
	v_mov_b32_e32 v5, v1
	v_mov_b32_e32 v6, v1
	v_mov_b32_e32 v7, v1
	v_mov_b32_e32 v8, v1
	v_mov_b32_e32 v9, v1
	v_mov_b32_e32 v10, v1
	v_mov_b32_e32 v11, v1
	v_mov_b32_e32 v12, v1
	v_mov_b32_e32 v13, v1
	v_mov_b64_e32 v[30:31], v[14:15]
	v_mov_b64_e32 v[46:47], v[14:15]
	v_mov_b64_e32 v[62:63], v[14:15]
	v_mov_b64_e32 v[78:79], v[14:15]
	s_mov_b32 s8, 3
	s_mov_b32 s53, s91
	v_mov_b32_e32 v223, v221
	v_mov_b64_e32 v[28:29], v[12:13]
	v_mov_b64_e32 v[26:27], v[10:11]
	v_mov_b64_e32 v[24:25], v[8:9]
	v_mov_b64_e32 v[22:23], v[6:7]
	v_mov_b64_e32 v[20:21], v[4:5]
	v_mov_b64_e32 v[18:19], v[2:3]
	v_mov_b64_e32 v[16:17], v[0:1]
	v_mov_b64_e32 v[44:45], v[12:13]
	v_mov_b64_e32 v[42:43], v[10:11]
	v_mov_b64_e32 v[40:41], v[8:9]
	v_mov_b64_e32 v[38:39], v[6:7]
	s_cmp_lg_u32 s99, 0
	s_cbranch_scc1 .Lmx_pw
	s_waitcnt vmcnt(0)
.Lmx_pw:
	s_cmp_lg_u32 s99, 0
	s_cbranch_scc1 .Lmx_pb
	s_waitcnt vmcnt(0)
.Lmx_pb:
	s_waitcnt lgkmcnt(0)
	s_barrier
	v_mov_b64_e32 v[36:37], v[4:5]
	v_mov_b64_e32 v[34:35], v[2:3]
	v_mov_b64_e32 v[32:33], v[0:1]
	v_mov_b64_e32 v[60:61], v[12:13]
	v_mov_b64_e32 v[58:59], v[10:11]
	v_mov_b64_e32 v[56:57], v[8:9]
	v_mov_b64_e32 v[54:55], v[6:7]
	v_mov_b64_e32 v[52:53], v[4:5]
	v_mov_b64_e32 v[50:51], v[2:3]
	v_mov_b64_e32 v[48:49], v[0:1]
	v_mov_b64_e32 v[76:77], v[12:13]
	v_mov_b64_e32 v[74:75], v[10:11]
	v_mov_b64_e32 v[72:73], v[8:9]
	v_mov_b64_e32 v[70:71], v[6:7]
	v_mov_b64_e32 v[68:69], v[4:5]
	v_mov_b64_e32 v[66:67], v[2:3]
	v_mov_b64_e32 v[64:65], v[0:1]
	v_mov_b32_e32 v224, 0
	v_mov_b32_e32 v0, 0
	v_mov_b32_e32 v225, 0
	s_mov_b32 s10, 0
	s_branch .LBB0_428

; __device__ __forceinline__ void flash_da2(LAS unsigned char* lds, const bf16* __restrict__ Qw, const bf16* __restrict__ Kb, const bf16* __restrict__ VTb,
;                                           int NT, int qpos_w, f32x16 (&o)[4], float& mref, float& lsum) {
;     ...
;     for (int d0 = 0; d0 < 4; ++d0) qf[d0] = *(const bf16x8*)(Qw + (size_t)r32 * 64 + d0 * 16 + hi * 8);
;     ...
;         da_tile<true>(lds, t, NT, qpos_w, r32, hi, qf, kaddr, vaddr, ksrc, vsrc, kdst, vdst, cls_cur, cb, o, mref, lsum);
;         da_tile<false>(lds, t + 1, NT, qpos_w, r32, hi, qf, kaddr, vaddr, ksrc, vsrc, kdst, vdst, cls_cur, cb, o, mref, lsum);
.LBB0_448:
	s_cmp_ge_u32 s66, s90
	s_cbranch_scc0 .Lmx_qno
	s_cmp_lg_u32 s99, 0
	s_cbranch_scc1 .Lmx_qno
	v_lshl_add_u64 v[246:247], v[158:159], 0, s[100:101]
	global_load_dwordx4 v[112:115], v[246:247], off
	global_load_dwordx4 v[116:119], v[246:247], off offset:32
	global_load_dwordx4 v[120:123], v[246:247], off offset:64
	global_load_dwordx4 v[124:127], v[246:247], off offset:96

; template <bool ISSUE> ...
;     ...
;     if (ISSUE) {
;         if (t + 2 < NT) {
;             glds16(ksrc + (size_t)(t + 2) * 4096, (unsigned)__builtin_amdgcn_readfirstlane(kdst + ((t + 2) & 3) * 8192));
;             glds16(vsrc + (size_t)(t + 2) * 8192, (unsigned)__builtin_amdgcn_readfirstlane(vdst + ((t + 2) & 3) * 16384));
;             glds16(vsrc + (size_t)(t + 2) * 8192 + 4096, (unsigned)__builtin_amdgcn_readfirstlane(vdst + ((t + 2) & 3) * 16384 + 8192));
;             glds16(ksrc + (size_t)(t + 3) * 4096, (unsigned)__builtin_amdgcn_readfirstlane(kdst + ((t + 3) & 3) * 8192));
;             glds16(vsrc + (size_t)(t + 3) * 8192, (unsigned)__builtin_amdgcn_readfirstlane(vdst + ((t + 3) & 3) * 16384));
;             glds16(vsrc + (size_t)(t + 3) * 8192 + 4096, (unsigned)__builtin_amdgcn_readfirstlane(vdst + ((t + 3) & 3) * 16384 + 8192));
;         }
; __device__ __forceinline__ void flash_da2(LAS unsigned char* lds, const bf16* __restrict__ Qw, const bf16* __restrict__ Kb, const bf16* __restrict__ VTb,
;                                           int NT, int qpos_w, f32x16 (&o)[4], float& mref, float& lsum) {
;     ...
;         glds16(ksrc + (size_t)j * 4096, (unsigned)__builtin_amdgcn_readfirstlane(kdst + j * 8192));
;         glds16(vsrc + (size_t)j * 8192, (unsigned)__builtin_amdgcn_readfirstlane(vdst + j * 16384));
;         glds16(vsrc + (size_t)j * 8192 + 4096, (unsigned)__builtin_amdgcn_readfirstlane(vdst + j * 16384 + 8192));
.Lmx_tail:
	s_cmp_lg_u32 s99, 0
	s_cbranch_scc1 .LBB0_440
	s_mov_b32 s100, s51
	s_mov_b32 s101, 0
	s_lshl_b64 s[100:101], s[100:101], 1
	s_mov_b32 s98, m0
	v_lshl_add_u64 v[14:15], v[246:247], 0, s[100:101]
	s_add_i32 m0, s35, 0x0
	s_nop 0
	global_load_lds_dwordx4 v[14:15], off
	s_add_i32 m0, s35, 0x8000
	s_nop 0
	global_load_lds_dwordx4 v[248:249], off
	v_lshl_add_u64 v[246:247], v[248:249], 0, s[38:39]
	s_add_i32 m0, s35, 0xa000
	s_nop 0
	global_load_lds_dwordx4 v[246:247], off
	v_lshl_add_u64 v[14:15], v[14:15], 0, s[38:39]
	s_add_i32 m0, s35, 0x2000
	s_nop 0
	global_load_lds_dwordx4 v[14:15], off
	v_lshl_add_u64 v[246:247], v[248:249], 0, s[40:41]
	s_add_i32 m0, s35, 0xc000
	s_nop 0
	global_load_lds_dwordx4 v[246:247], off
	v_lshl_add_u64 v[14:15], v[248:249], 0, s[42:43]
	s_add_i32 m0, s35, 0xe000
	s_nop 0
	global_load_lds_dwordx4 v[14:15], off
	s_mov_b32 m0, s98
	s_branch .LBB0_440

; __device__ __forceinline__ float hsum(float v) { auto rr = __builtin_amdgcn_permlane32_swap(__float_as_uint(v), __float_as_uint(v), false, false); return __uint_as_float(rr[0]) + __uint_as_float(rr[1]); }
; __device__ __forceinline__ void da_unit(LAS unsigned char* lds, const AttnP& P, int seqbase, int S, int h, int qb, float lam) {
;     ...
;         if (map == 0) {
;             const float inv = 1.0f / hsum(l);
; #pragma unroll
;             for (int db = 0; db < 4; ++db)
; #pragma unroll
;                 for (int g = 0; g < 4; ++g) stash[db * 4 + g] = (f32x4){o[db][4 * g], o[db][4 * g + 1], o[db][4 * g + 2], o[db][4 * g + 3]} * inv;
.LBB0_452:
	v_mov_b32_e32 v129, v67
	v_mov_b32_e32 v128, v66
	v_mov_b32_e32 v131, v65
	v_mov_b32_e32 v130, v64
	v_mov_b32_e32 v91, v63
	v_mov_b32_e32 v90, v62
	v_mov_b32_e32 v93, v61
	v_mov_b32_e32 v92, v60
	v_mov_b32_e32 v97, v59
	v_mov_b32_e32 v96, v58
	v_mov_b32_e32 v107, v57
	v_mov_b32_e32 v106, v56
	v_mov_b32_e32 v109, v55
	v_mov_b32_e32 v108, v54
	v_mov_b32_e32 v111, v53
	v_mov_b32_e32 v110, v52
	v_mov_b32_e32 v5, v47
	v_mov_b32_e32 v4, v46
	v_mov_b32_e32 v7, v45
	v_mov_b32_e32 v6, v44
	v_mov_b32_e32 v9, v43
	v_mov_b32_e32 v8, v42
	v_mov_b32_e32 v11, v41
	v_mov_b32_e32 v10, v40
	v_mov_b32_e32 v13, v39
	v_mov_b32_e32 v12, v38
	v_mov_b32_e32 v15, v37
	v_mov_b32_e32 v14, v36
	v_mov_b32_e32 v87, v35
	v_mov_b32_e32 v86, v34
	v_mov_b32_e32 v95, v33
	v_mov_b32_e32 v94, v32
	v_mov_b32_e32 v83, v31
	v_mov_b32_e32 v82, v30
	v_mov_b32_e32 v81, v29
	v_mov_b32_e32 v80, v28
	v_mov_b32_e32 v85, v27
	v_mov_b32_e32 v84, v26
	v_mov_b32_e32 v89, v25
	v_mov_b32_e32 v88, v24
	v_mov_b32_e32 v101, v23
	v_mov_b32_e32 v100, v22
	v_mov_b32_e32 v99, v21
	v_mov_b32_e32 v98, v20
	v_mov_b32_e32 v105, v19
	v_mov_b32_e32 v104, v18
	v_mov_b32_e32 v103, v17
	v_mov_b32_e32 v102, v16
